# PEER pass 1: rows double-buffered one token ahead + transposing butterfly reduce (DPP) in the column-sliced pass
# speedup vs baseline: 1.0204x; 1.0070x over previous
.Lpu_pass1:
	v_and_b32_e32 v5, 7, v167
	v_lshlrev_b32_e32 v1, 4, v5
	v_lshlrev_b32_e32 v2, 5, v5
	v_lshrrev_b32_e32 v4, 3, v167
	v_lshl_or_b32 v3, v5, 3, v4
	v_lshlrev_b32_e32 v3, 2, v3
	v_lshlrev_b32_e32 v4, 2, v4
	v_lshlrev_b32_e32 v6, 2, v167
	v_add_u32_e32 v12, 32, v4
	v_add_u32_e32 v13, 64, v4
	v_add_u32_e32 v14, 96, v4
	v_add_u32_e32 v15, 128, v4
	v_add_u32_e32 v16, 160, v4
	v_add_u32_e32 v17, 192, v4
	v_add_u32_e32 v18, 224, v4
	v_and_b32_e32 v7, 1, v167
	v_cmp_ne_u32_e64 s[30:31], 0, v7
	v_and_b32_e32 v7, 2, v167
	v_cmp_ne_u32_e64 s[34:35], 0, v7
	v_and_b32_e32 v7, 4, v167
	v_cmp_ne_u32_e32 vcc, 0, v7
	v_mov_b32_e32 v7, 0x26c08
	ds_read_b32 v8, v7
	ds_read_b32 v9, v7 offset:4
	v_add_u32_e32 v10, 0x670b800, v6
	global_load_dword v11, v10, s[66:67] sc1
	s_waitcnt vmcnt(0) lgkmcnt(0)
	v_readfirstlane_b32 s0, v8
	v_readfirstlane_b32 s1, v9
	v_cmp_ne_u32_e64 s[20:21], 0, v11
	s_nop 3
	s_and_b32 s20, s20, 0xffff
	s_bcnt1_i32_b32 s41, s20
	s_bfm_b32 s21, s0, 0
	s_and_b32 s21, s21, s20
	s_bcnt1_i32_b32 s40, s21
	s_nop 3
	v_readlane_b32 s39, v11, s0
	v_readfirstlane_b32 s20, v135
	s_nop 3
	s_lshl_b32 s39, s39, 3
	s_max_u32 s39, s39, 8
	s_max_u32 s41, s41, 1
	s_lshr_b32 s20, s20, 6
	s_lshl_b32 s1, s1, 3
	s_add_i32 s51, s1, s20
	s_add_u32 s42, s66, 0x20b6c000
	s_addc_u32 s43, s67, 0
.Lpu_part:
	s_cmp_gt_u32 s40, 7
	s_cbranch_scc1 .Lpu_done
	s_lshl_b32 s0, s40, 21
	s_add_u32 s44, s66, s0
	s_addc_u32 s45, s67, 0
	s_add_u32 s44, s44, 0x2010000
	s_addc_u32 s45, s45, 0
	s_lshl_b32 s0, s40, 25
	s_add_u32 s46, s66, s0
	s_addc_u32 s47, s67, 0
	s_add_u32 s46, s46, 0x25f6c000
	s_addc_u32 s47, s47, 0
	s_lshl_b32 s0, s40, 8
	s_add_u32 s48, s66, s0
	s_addc_u32 s49, s67, 0
	s_add_u32 s48, s48, 0x8b6c000
	s_addc_u32 s49, s49, 0
	s_mov_b32 s38, s51
	s_lshl_b32 s0, s38, 9
	v_add_u32_e32 v0, s0, v6
	global_load_dword v10, v0, s[42:43]
	global_load_dword v11, v0, s[42:43] offset:256
	s_lshl_b32 s0, s38, 11
	v_add_u32_e32 v0, s0, v2
	global_load_dwordx4 v[20:23], v0, s[48:49]
	global_load_dwordx4 v[24:27], v0, s[48:49] offset:16
	s_waitcnt vmcnt(0)
	v_lshlrev_b32_e32 v28, 16, v20
	v_and_b32_e32 v29, 0xffff0000, v20
	v_lshlrev_b32_e32 v30, 16, v21
	v_and_b32_e32 v31, 0xffff0000, v21
	v_lshlrev_b32_e32 v32, 16, v22
	v_and_b32_e32 v33, 0xffff0000, v22
	v_lshlrev_b32_e32 v34, 16, v23
	v_and_b32_e32 v35, 0xffff0000, v23
	v_lshlrev_b32_e32 v36, 16, v24
	v_and_b32_e32 v37, 0xffff0000, v24
	v_lshlrev_b32_e32 v38, 16, v25
	v_and_b32_e32 v39, 0xffff0000, v25
	v_lshlrev_b32_e32 v40, 16, v26
	v_and_b32_e32 v41, 0xffff0000, v26
	v_lshlrev_b32_e32 v42, 16, v27
	v_and_b32_e32 v43, 0xffff0000, v27
	ds_bpermute_b32 v124, v4, v10
	ds_bpermute_b32 v125, v12, v10
	ds_bpermute_b32 v126, v13, v10
	ds_bpermute_b32 v127, v14, v10
	ds_bpermute_b32 v128, v15, v10
	ds_bpermute_b32 v129, v16, v10
	ds_bpermute_b32 v130, v17, v10
	ds_bpermute_b32 v131, v18, v10
	s_waitcnt lgkmcnt(0)
	v_lshl_add_u32 v124, v124, 7, v1
	v_lshl_add_u32 v125, v125, 7, v1
	v_lshl_add_u32 v126, v126, 7, v1
	v_lshl_add_u32 v127, v127, 7, v1
	v_lshl_add_u32 v128, v128, 7, v1
	v_lshl_add_u32 v129, v129, 7, v1
	v_lshl_add_u32 v130, v130, 7, v1
	v_lshl_add_u32 v131, v131, 7, v1
	global_load_dwordx4 v[44:47], v124, s[44:45]
	global_load_dwordx4 v[48:51], v125, s[44:45]
	global_load_dwordx4 v[52:55], v126, s[44:45]
	global_load_dwordx4 v[56:59], v127, s[44:45]
	global_load_dwordx4 v[60:63], v128, s[44:45]
	global_load_dwordx4 v[64:67], v129, s[44:45]
	global_load_dwordx4 v[68:71], v130, s[44:45]
	global_load_dwordx4 v[72:75], v131, s[44:45]
	ds_bpermute_b32 v124, v4, v11
	ds_bpermute_b32 v125, v12, v11
	ds_bpermute_b32 v126, v13, v11
	ds_bpermute_b32 v127, v14, v11
	ds_bpermute_b32 v128, v15, v11
	ds_bpermute_b32 v129, v16, v11
	ds_bpermute_b32 v130, v17, v11
	ds_bpermute_b32 v131, v18, v11
	s_waitcnt lgkmcnt(0)
	v_lshl_add_u32 v124, v124, 7, v1
	v_lshl_add_u32 v125, v125, 7, v1
	v_lshl_add_u32 v126, v126, 7, v1
	v_lshl_add_u32 v127, v127, 7, v1
	v_lshl_add_u32 v128, v128, 7, v1
	v_lshl_add_u32 v129, v129, 7, v1
	v_lshl_add_u32 v130, v130, 7, v1
	v_lshl_add_u32 v131, v131, 7, v1
	global_load_dwordx4 v[76:79], v124, s[44:45]
	global_load_dwordx4 v[80:83], v125, s[44:45]
	global_load_dwordx4 v[84:87], v126, s[44:45]
	global_load_dwordx4 v[88:91], v127, s[44:45]
	global_load_dwordx4 v[92:95], v128, s[44:45]
	global_load_dwordx4 v[96:99], v129, s[44:45]
	global_load_dwordx4 v[100:103], v130, s[44:45]
	global_load_dwordx4 v[104:107], v131, s[44:45]
	s_add_i32 s1, s38, s39
	s_min_u32 s1, s1, 0xffff
	s_lshl_b32 s0, s1, 9
	v_add_u32_e32 v0, s0, v6
	global_load_dword v10, v0, s[42:43]
	global_load_dword v11, v0, s[42:43] offset:256
	s_lshl_b32 s0, s1, 11
	v_add_u32_e32 v0, s0, v2
	global_load_dwordx4 v[20:23], v0, s[48:49]
	global_load_dwordx4 v[24:27], v0, s[48:49] offset:16
	s_waitcnt vmcnt(0)
	s_branch .Lpu_tokA_in
.Lpu_tokA:
	s_waitcnt vmcnt(2)
.Lpu_tokA_in:
	v_lshlrev_b32_e32 v108, 16, v20
	v_and_b32_e32 v109, 0xffff0000, v20
	v_lshlrev_b32_e32 v110, 16, v21
	v_and_b32_e32 v111, 0xffff0000, v21
	v_lshlrev_b32_e32 v112, 16, v22
	v_and_b32_e32 v113, 0xffff0000, v22
	v_lshlrev_b32_e32 v114, 16, v23
	v_and_b32_e32 v115, 0xffff0000, v23
	v_lshlrev_b32_e32 v238, 16, v24
	v_and_b32_e32 v239, 0xffff0000, v24
	v_lshlrev_b32_e32 v240, 16, v25
	v_and_b32_e32 v241, 0xffff0000, v25
	v_lshlrev_b32_e32 v242, 16, v26
	v_and_b32_e32 v243, 0xffff0000, v26
	v_lshlrev_b32_e32 v244, 16, v27
	v_and_b32_e32 v245, 0xffff0000, v27
	ds_bpermute_b32 v124, v4, v10
	ds_bpermute_b32 v125, v12, v10
	ds_bpermute_b32 v126, v13, v10
	ds_bpermute_b32 v127, v14, v10
	ds_bpermute_b32 v128, v15, v10
	ds_bpermute_b32 v129, v16, v10
	ds_bpermute_b32 v130, v17, v10
	ds_bpermute_b32 v131, v18, v10
	s_waitcnt lgkmcnt(0)
	v_lshl_add_u32 v124, v124, 7, v1
	v_lshl_add_u32 v125, v125, 7, v1
	v_lshl_add_u32 v126, v126, 7, v1
	v_lshl_add_u32 v127, v127, 7, v1
	v_lshl_add_u32 v128, v128, 7, v1
	v_lshl_add_u32 v129, v129, 7, v1
	v_lshl_add_u32 v130, v130, 7, v1
	v_lshl_add_u32 v131, v131, 7, v1
	global_load_dwordx4 v[198:201], v124, s[44:45]
	global_load_dwordx4 v[202:205], v125, s[44:45]
	global_load_dwordx4 v[206:209], v126, s[44:45]
	global_load_dwordx4 v[210:213], v127, s[44:45]
	global_load_dwordx4 v[214:217], v128, s[44:45]
	global_load_dwordx4 v[218:221], v129, s[44:45]
	global_load_dwordx4 v[222:225], v130, s[44:45]
	global_load_dwordx4 v[226:229], v131, s[44:45]
	ds_bpermute_b32 v124, v4, v11
	ds_bpermute_b32 v125, v12, v11
	ds_bpermute_b32 v126, v13, v11
	ds_bpermute_b32 v127, v14, v11
	ds_bpermute_b32 v128, v15, v11
	ds_bpermute_b32 v129, v16, v11
	ds_bpermute_b32 v130, v17, v11
	ds_bpermute_b32 v131, v18, v11
	s_waitcnt lgkmcnt(0)
	v_lshl_add_u32 v124, v124, 7, v1
	v_lshl_add_u32 v125, v125, 7, v1
	v_lshl_add_u32 v126, v126, 7, v1
	v_lshl_add_u32 v127, v127, 7, v1
	v_lshl_add_u32 v128, v128, 7, v1
	v_lshl_add_u32 v129, v129, 7, v1
	v_lshl_add_u32 v130, v130, 7, v1
	v_lshl_add_u32 v131, v131, 7, v1
	global_load_dwordx4 v[230:233], v124, s[44:45]
	global_load_dwordx4 v[234:237], v125, s[44:45]
	global_load_dwordx4 v[138:141], v126, s[44:45]
	global_load_dwordx4 v[142:145], v127, s[44:45]
	global_load_dwordx4 v[146:149], v128, s[44:45]
	global_load_dwordx4 v[150:153], v129, s[44:45]
	global_load_dwordx4 v[154:157], v130, s[44:45]
	global_load_dwordx4 v[158:161], v131, s[44:45]
	s_lshl_b32 s1, s39, 1
	s_add_i32 s1, s1, s38
	s_min_u32 s1, s1, 0xffff
	s_lshl_b32 s0, s1, 9
	v_add_u32_e32 v0, s0, v6
	global_load_dword v10, v0, s[42:43]
	global_load_dword v11, v0, s[42:43] offset:256
	s_lshl_b32 s0, s1, 11
	v_add_u32_e32 v0, s0, v2
	global_load_dwordx4 v[20:23], v0, s[48:49]
	global_load_dwordx4 v[24:27], v0, s[48:49] offset:16
	v_cvt_pk_f32_fp8_e32 v[118:119], v44
	v_cvt_pk_f32_fp8_sdwa v[120:121], v44 src0_sel:WORD_1
	s_nop 0
	v_pk_mul_f32 v[8:9], v[118:119], v[28:29]
	v_cvt_pk_f32_fp8_e32 v[118:119], v45
	v_pk_fma_f32 v[8:9], v[120:121], v[30:31], v[8:9]
	v_cvt_pk_f32_fp8_sdwa v[120:121], v45 src0_sel:WORD_1
	v_pk_fma_f32 v[8:9], v[118:119], v[32:33], v[8:9]
	v_cvt_pk_f32_fp8_e32 v[118:119], v46
	v_pk_fma_f32 v[8:9], v[120:121], v[34:35], v[8:9]
	v_cvt_pk_f32_fp8_sdwa v[120:121], v46 src0_sel:WORD_1
	v_pk_fma_f32 v[8:9], v[118:119], v[36:37], v[8:9]
	v_cvt_pk_f32_fp8_e32 v[118:119], v47
	v_pk_fma_f32 v[8:9], v[120:121], v[38:39], v[8:9]
	v_cvt_pk_f32_fp8_sdwa v[120:121], v47 src0_sel:WORD_1
	v_pk_fma_f32 v[8:9], v[118:119], v[40:41], v[8:9]
	s_nop 0
	v_pk_fma_f32 v[8:9], v[120:121], v[42:43], v[8:9]
	v_add_f32_e32 v124, v8, v9
	v_cvt_pk_f32_fp8_e32 v[118:119], v48
	v_cvt_pk_f32_fp8_sdwa v[120:121], v48 src0_sel:WORD_1
	s_nop 0
	v_pk_mul_f32 v[8:9], v[118:119], v[28:29]
	v_cvt_pk_f32_fp8_e32 v[118:119], v49
	v_pk_fma_f32 v[8:9], v[120:121], v[30:31], v[8:9]
	v_cvt_pk_f32_fp8_sdwa v[120:121], v49 src0_sel:WORD_1
	v_pk_fma_f32 v[8:9], v[118:119], v[32:33], v[8:9]
	v_cvt_pk_f32_fp8_e32 v[118:119], v50
	v_pk_fma_f32 v[8:9], v[120:121], v[34:35], v[8:9]
	v_cvt_pk_f32_fp8_sdwa v[120:121], v50 src0_sel:WORD_1
	v_pk_fma_f32 v[8:9], v[118:119], v[36:37], v[8:9]
	v_cvt_pk_f32_fp8_e32 v[118:119], v51
	v_pk_fma_f32 v[8:9], v[120:121], v[38:39], v[8:9]
	v_cvt_pk_f32_fp8_sdwa v[120:121], v51 src0_sel:WORD_1
	v_pk_fma_f32 v[8:9], v[118:119], v[40:41], v[8:9]
	s_nop 0
	v_pk_fma_f32 v[8:9], v[120:121], v[42:43], v[8:9]
	v_add_f32_e32 v125, v8, v9
	v_cvt_pk_f32_fp8_e32 v[118:119], v52
	v_cvt_pk_f32_fp8_sdwa v[120:121], v52 src0_sel:WORD_1
	s_nop 0
	v_pk_mul_f32 v[8:9], v[118:119], v[28:29]
	v_cvt_pk_f32_fp8_e32 v[118:119], v53
	v_pk_fma_f32 v[8:9], v[120:121], v[30:31], v[8:9]
	v_cvt_pk_f32_fp8_sdwa v[120:121], v53 src0_sel:WORD_1
	v_pk_fma_f32 v[8:9], v[118:119], v[32:33], v[8:9]
	v_cvt_pk_f32_fp8_e32 v[118:119], v54
	v_pk_fma_f32 v[8:9], v[120:121], v[34:35], v[8:9]
	v_cvt_pk_f32_fp8_sdwa v[120:121], v54 src0_sel:WORD_1
	v_pk_fma_f32 v[8:9], v[118:119], v[36:37], v[8:9]
	v_cvt_pk_f32_fp8_e32 v[118:119], v55
	v_pk_fma_f32 v[8:9], v[120:121], v[38:39], v[8:9]
	v_cvt_pk_f32_fp8_sdwa v[120:121], v55 src0_sel:WORD_1
	v_pk_fma_f32 v[8:9], v[118:119], v[40:41], v[8:9]
	s_nop 0
	v_pk_fma_f32 v[8:9], v[120:121], v[42:43], v[8:9]
	v_add_f32_e32 v126, v8, v9
	v_cvt_pk_f32_fp8_e32 v[118:119], v56
	v_cvt_pk_f32_fp8_sdwa v[120:121], v56 src0_sel:WORD_1
	s_nop 0
	v_pk_mul_f32 v[8:9], v[118:119], v[28:29]
	v_cvt_pk_f32_fp8_e32 v[118:119], v57
	v_pk_fma_f32 v[8:9], v[120:121], v[30:31], v[8:9]
	v_cvt_pk_f32_fp8_sdwa v[120:121], v57 src0_sel:WORD_1
	v_pk_fma_f32 v[8:9], v[118:119], v[32:33], v[8:9]
	v_cvt_pk_f32_fp8_e32 v[118:119], v58
	v_pk_fma_f32 v[8:9], v[120:121], v[34:35], v[8:9]
	v_cvt_pk_f32_fp8_sdwa v[120:121], v58 src0_sel:WORD_1
	v_pk_fma_f32 v[8:9], v[118:119], v[36:37], v[8:9]
	v_cvt_pk_f32_fp8_e32 v[118:119], v59
	v_pk_fma_f32 v[8:9], v[120:121], v[38:39], v[8:9]
	v_cvt_pk_f32_fp8_sdwa v[120:121], v59 src0_sel:WORD_1
	v_pk_fma_f32 v[8:9], v[118:119], v[40:41], v[8:9]
	s_nop 0
	v_pk_fma_f32 v[8:9], v[120:121], v[42:43], v[8:9]
	v_add_f32_e32 v127, v8, v9
	v_cvt_pk_f32_fp8_e32 v[118:119], v60
	v_cvt_pk_f32_fp8_sdwa v[120:121], v60 src0_sel:WORD_1
	s_nop 0
	v_pk_mul_f32 v[8:9], v[118:119], v[28:29]
	v_cvt_pk_f32_fp8_e32 v[118:119], v61
	v_pk_fma_f32 v[8:9], v[120:121], v[30:31], v[8:9]
	v_cvt_pk_f32_fp8_sdwa v[120:121], v61 src0_sel:WORD_1
	v_pk_fma_f32 v[8:9], v[118:119], v[32:33], v[8:9]
	v_cvt_pk_f32_fp8_e32 v[118:119], v62
	v_pk_fma_f32 v[8:9], v[120:121], v[34:35], v[8:9]
	v_cvt_pk_f32_fp8_sdwa v[120:121], v62 src0_sel:WORD_1
	v_pk_fma_f32 v[8:9], v[118:119], v[36:37], v[8:9]
	v_cvt_pk_f32_fp8_e32 v[118:119], v63
	v_pk_fma_f32 v[8:9], v[120:121], v[38:39], v[8:9]
	v_cvt_pk_f32_fp8_sdwa v[120:121], v63 src0_sel:WORD_1
	v_pk_fma_f32 v[8:9], v[118:119], v[40:41], v[8:9]
	s_nop 0
	v_pk_fma_f32 v[8:9], v[120:121], v[42:43], v[8:9]
	v_add_f32_e32 v128, v8, v9
	v_cvt_pk_f32_fp8_e32 v[118:119], v64
	v_cvt_pk_f32_fp8_sdwa v[120:121], v64 src0_sel:WORD_1
	s_nop 0
	v_pk_mul_f32 v[8:9], v[118:119], v[28:29]
	v_cvt_pk_f32_fp8_e32 v[118:119], v65
	v_pk_fma_f32 v[8:9], v[120:121], v[30:31], v[8:9]
	v_cvt_pk_f32_fp8_sdwa v[120:121], v65 src0_sel:WORD_1
	v_pk_fma_f32 v[8:9], v[118:119], v[32:33], v[8:9]
	v_cvt_pk_f32_fp8_e32 v[118:119], v66
	v_pk_fma_f32 v[8:9], v[120:121], v[34:35], v[8:9]
	v_cvt_pk_f32_fp8_sdwa v[120:121], v66 src0_sel:WORD_1
	v_pk_fma_f32 v[8:9], v[118:119], v[36:37], v[8:9]
	v_cvt_pk_f32_fp8_e32 v[118:119], v67
	v_pk_fma_f32 v[8:9], v[120:121], v[38:39], v[8:9]
	v_cvt_pk_f32_fp8_sdwa v[120:121], v67 src0_sel:WORD_1
	v_pk_fma_f32 v[8:9], v[118:119], v[40:41], v[8:9]
	s_nop 0
	v_pk_fma_f32 v[8:9], v[120:121], v[42:43], v[8:9]
	v_add_f32_e32 v129, v8, v9
	v_cvt_pk_f32_fp8_e32 v[118:119], v68
	v_cvt_pk_f32_fp8_sdwa v[120:121], v68 src0_sel:WORD_1
	s_nop 0
	v_pk_mul_f32 v[8:9], v[118:119], v[28:29]
	v_cvt_pk_f32_fp8_e32 v[118:119], v69
	v_pk_fma_f32 v[8:9], v[120:121], v[30:31], v[8:9]
	v_cvt_pk_f32_fp8_sdwa v[120:121], v69 src0_sel:WORD_1
	v_pk_fma_f32 v[8:9], v[118:119], v[32:33], v[8:9]
	v_cvt_pk_f32_fp8_e32 v[118:119], v70
	v_pk_fma_f32 v[8:9], v[120:121], v[34:35], v[8:9]
	v_cvt_pk_f32_fp8_sdwa v[120:121], v70 src0_sel:WORD_1
	v_pk_fma_f32 v[8:9], v[118:119], v[36:37], v[8:9]
	v_cvt_pk_f32_fp8_e32 v[118:119], v71
	v_pk_fma_f32 v[8:9], v[120:121], v[38:39], v[8:9]
	v_cvt_pk_f32_fp8_sdwa v[120:121], v71 src0_sel:WORD_1
	v_pk_fma_f32 v[8:9], v[118:119], v[40:41], v[8:9]
	s_nop 0
	v_pk_fma_f32 v[8:9], v[120:121], v[42:43], v[8:9]
	v_add_f32_e32 v130, v8, v9
	v_cvt_pk_f32_fp8_e32 v[118:119], v72
	v_cvt_pk_f32_fp8_sdwa v[120:121], v72 src0_sel:WORD_1
	s_nop 0
	v_pk_mul_f32 v[8:9], v[118:119], v[28:29]
	v_cvt_pk_f32_fp8_e32 v[118:119], v73
	v_pk_fma_f32 v[8:9], v[120:121], v[30:31], v[8:9]
	v_cvt_pk_f32_fp8_sdwa v[120:121], v73 src0_sel:WORD_1
	v_pk_fma_f32 v[8:9], v[118:119], v[32:33], v[8:9]
	v_cvt_pk_f32_fp8_e32 v[118:119], v74
	v_pk_fma_f32 v[8:9], v[120:121], v[34:35], v[8:9]
	v_cvt_pk_f32_fp8_sdwa v[120:121], v74 src0_sel:WORD_1
	v_pk_fma_f32 v[8:9], v[118:119], v[36:37], v[8:9]
	v_cvt_pk_f32_fp8_e32 v[118:119], v75
	v_pk_fma_f32 v[8:9], v[120:121], v[38:39], v[8:9]
	v_cvt_pk_f32_fp8_sdwa v[120:121], v75 src0_sel:WORD_1
	v_pk_fma_f32 v[8:9], v[118:119], v[40:41], v[8:9]
	s_nop 0
	v_pk_fma_f32 v[8:9], v[120:121], v[42:43], v[8:9]
	v_add_f32_e32 v131, v8, v9
	v_cndmask_b32_e32 v116, v124, v128, vcc
	v_cndmask_b32_e32 v117, v128, v124, vcc
	v_cndmask_b32_e32 v118, v125, v129, vcc
	v_cndmask_b32_e32 v119, v129, v125, vcc
	v_cndmask_b32_e32 v120, v126, v130, vcc
	v_cndmask_b32_e32 v121, v130, v126, vcc
	v_cndmask_b32_e32 v122, v127, v131, vcc
	v_cndmask_b32_e32 v123, v131, v127, vcc
	v_add_f32_dpp v124, v117, v116 row_half_mirror row_mask:0xf bank_mask:0xf
	v_add_f32_dpp v125, v119, v118 row_half_mirror row_mask:0xf bank_mask:0xf
	v_add_f32_dpp v126, v121, v120 row_half_mirror row_mask:0xf bank_mask:0xf
	v_add_f32_dpp v127, v123, v122 row_half_mirror row_mask:0xf bank_mask:0xf
	v_cndmask_b32_e64 v116, v124, v126, s[34:35]
	v_cndmask_b32_e64 v117, v126, v124, s[34:35]
	v_cndmask_b32_e64 v118, v125, v127, s[34:35]
	v_cndmask_b32_e64 v119, v127, v125, s[34:35]
	s_nop 0
	v_add_f32_dpp v124, v117, v116 quad_perm:[2,3,0,1] row_mask:0xf bank_mask:0xf
	v_add_f32_dpp v125, v119, v118 quad_perm:[2,3,0,1] row_mask:0xf bank_mask:0xf
	v_cndmask_b32_e64 v116, v124, v125, s[30:31]
	v_cndmask_b32_e64 v117, v125, v124, s[30:31]
	s_nop 1
	v_add_f32_dpp v5, v117, v116 quad_perm:[1,0,3,2] row_mask:0xf bank_mask:0xf
	v_cvt_pk_f32_fp8_e32 v[118:119], v76
	v_cvt_pk_f32_fp8_sdwa v[120:121], v76 src0_sel:WORD_1
	s_nop 0
	v_pk_mul_f32 v[8:9], v[118:119], v[28:29]
	v_cvt_pk_f32_fp8_e32 v[118:119], v77
	v_pk_fma_f32 v[8:9], v[120:121], v[30:31], v[8:9]
	v_cvt_pk_f32_fp8_sdwa v[120:121], v77 src0_sel:WORD_1
	v_pk_fma_f32 v[8:9], v[118:119], v[32:33], v[8:9]
	v_cvt_pk_f32_fp8_e32 v[118:119], v78
	v_pk_fma_f32 v[8:9], v[120:121], v[34:35], v[8:9]
	v_cvt_pk_f32_fp8_sdwa v[120:121], v78 src0_sel:WORD_1
	v_pk_fma_f32 v[8:9], v[118:119], v[36:37], v[8:9]
	v_cvt_pk_f32_fp8_e32 v[118:119], v79
	v_pk_fma_f32 v[8:9], v[120:121], v[38:39], v[8:9]
	v_cvt_pk_f32_fp8_sdwa v[120:121], v79 src0_sel:WORD_1
	v_pk_fma_f32 v[8:9], v[118:119], v[40:41], v[8:9]
	s_nop 0
	v_pk_fma_f32 v[8:9], v[120:121], v[42:43], v[8:9]
	v_add_f32_e32 v124, v8, v9
	v_cvt_pk_f32_fp8_e32 v[118:119], v80
	v_cvt_pk_f32_fp8_sdwa v[120:121], v80 src0_sel:WORD_1
	s_nop 0
	v_pk_mul_f32 v[8:9], v[118:119], v[28:29]
	v_cvt_pk_f32_fp8_e32 v[118:119], v81
	v_pk_fma_f32 v[8:9], v[120:121], v[30:31], v[8:9]
	v_cvt_pk_f32_fp8_sdwa v[120:121], v81 src0_sel:WORD_1
	v_pk_fma_f32 v[8:9], v[118:119], v[32:33], v[8:9]
	v_cvt_pk_f32_fp8_e32 v[118:119], v82
	v_pk_fma_f32 v[8:9], v[120:121], v[34:35], v[8:9]
	v_cvt_pk_f32_fp8_sdwa v[120:121], v82 src0_sel:WORD_1
	v_pk_fma_f32 v[8:9], v[118:119], v[36:37], v[8:9]
	v_cvt_pk_f32_fp8_e32 v[118:119], v83
	v_pk_fma_f32 v[8:9], v[120:121], v[38:39], v[8:9]
	v_cvt_pk_f32_fp8_sdwa v[120:121], v83 src0_sel:WORD_1
	v_pk_fma_f32 v[8:9], v[118:119], v[40:41], v[8:9]
	s_nop 0
	v_pk_fma_f32 v[8:9], v[120:121], v[42:43], v[8:9]
	v_add_f32_e32 v125, v8, v9
	v_cvt_pk_f32_fp8_e32 v[118:119], v84
	v_cvt_pk_f32_fp8_sdwa v[120:121], v84 src0_sel:WORD_1
	s_nop 0
	v_pk_mul_f32 v[8:9], v[118:119], v[28:29]
	v_cvt_pk_f32_fp8_e32 v[118:119], v85
	v_pk_fma_f32 v[8:9], v[120:121], v[30:31], v[8:9]
	v_cvt_pk_f32_fp8_sdwa v[120:121], v85 src0_sel:WORD_1
	v_pk_fma_f32 v[8:9], v[118:119], v[32:33], v[8:9]
	v_cvt_pk_f32_fp8_e32 v[118:119], v86
	v_pk_fma_f32 v[8:9], v[120:121], v[34:35], v[8:9]
	v_cvt_pk_f32_fp8_sdwa v[120:121], v86 src0_sel:WORD_1
	v_pk_fma_f32 v[8:9], v[118:119], v[36:37], v[8:9]
	v_cvt_pk_f32_fp8_e32 v[118:119], v87
	v_pk_fma_f32 v[8:9], v[120:121], v[38:39], v[8:9]
	v_cvt_pk_f32_fp8_sdwa v[120:121], v87 src0_sel:WORD_1
	v_pk_fma_f32 v[8:9], v[118:119], v[40:41], v[8:9]
	s_nop 0
	v_pk_fma_f32 v[8:9], v[120:121], v[42:43], v[8:9]
	v_add_f32_e32 v126, v8, v9
	v_cvt_pk_f32_fp8_e32 v[118:119], v88
	v_cvt_pk_f32_fp8_sdwa v[120:121], v88 src0_sel:WORD_1
	s_nop 0
	v_pk_mul_f32 v[8:9], v[118:119], v[28:29]
	v_cvt_pk_f32_fp8_e32 v[118:119], v89
	v_pk_fma_f32 v[8:9], v[120:121], v[30:31], v[8:9]
	v_cvt_pk_f32_fp8_sdwa v[120:121], v89 src0_sel:WORD_1
	v_pk_fma_f32 v[8:9], v[118:119], v[32:33], v[8:9]
	v_cvt_pk_f32_fp8_e32 v[118:119], v90
	v_pk_fma_f32 v[8:9], v[120:121], v[34:35], v[8:9]
	v_cvt_pk_f32_fp8_sdwa v[120:121], v90 src0_sel:WORD_1
	v_pk_fma_f32 v[8:9], v[118:119], v[36:37], v[8:9]
	v_cvt_pk_f32_fp8_e32 v[118:119], v91
	v_pk_fma_f32 v[8:9], v[120:121], v[38:39], v[8:9]
	v_cvt_pk_f32_fp8_sdwa v[120:121], v91 src0_sel:WORD_1
	v_pk_fma_f32 v[8:9], v[118:119], v[40:41], v[8:9]
	s_nop 0
	v_pk_fma_f32 v[8:9], v[120:121], v[42:43], v[8:9]
	v_add_f32_e32 v127, v8, v9
	v_cvt_pk_f32_fp8_e32 v[118:119], v92
	v_cvt_pk_f32_fp8_sdwa v[120:121], v92 src0_sel:WORD_1
	s_nop 0
	v_pk_mul_f32 v[8:9], v[118:119], v[28:29]
	v_cvt_pk_f32_fp8_e32 v[118:119], v93
	v_pk_fma_f32 v[8:9], v[120:121], v[30:31], v[8:9]
	v_cvt_pk_f32_fp8_sdwa v[120:121], v93 src0_sel:WORD_1
	v_pk_fma_f32 v[8:9], v[118:119], v[32:33], v[8:9]
	v_cvt_pk_f32_fp8_e32 v[118:119], v94
	v_pk_fma_f32 v[8:9], v[120:121], v[34:35], v[8:9]
	v_cvt_pk_f32_fp8_sdwa v[120:121], v94 src0_sel:WORD_1
	v_pk_fma_f32 v[8:9], v[118:119], v[36:37], v[8:9]
	v_cvt_pk_f32_fp8_e32 v[118:119], v95
	v_pk_fma_f32 v[8:9], v[120:121], v[38:39], v[8:9]
	v_cvt_pk_f32_fp8_sdwa v[120:121], v95 src0_sel:WORD_1
	v_pk_fma_f32 v[8:9], v[118:119], v[40:41], v[8:9]
	s_nop 0
	v_pk_fma_f32 v[8:9], v[120:121], v[42:43], v[8:9]
	v_add_f32_e32 v128, v8, v9
	v_cvt_pk_f32_fp8_e32 v[118:119], v96
	v_cvt_pk_f32_fp8_sdwa v[120:121], v96 src0_sel:WORD_1
	s_nop 0
	v_pk_mul_f32 v[8:9], v[118:119], v[28:29]
	v_cvt_pk_f32_fp8_e32 v[118:119], v97
	v_pk_fma_f32 v[8:9], v[120:121], v[30:31], v[8:9]
	v_cvt_pk_f32_fp8_sdwa v[120:121], v97 src0_sel:WORD_1
	v_pk_fma_f32 v[8:9], v[118:119], v[32:33], v[8:9]
	v_cvt_pk_f32_fp8_e32 v[118:119], v98
	v_pk_fma_f32 v[8:9], v[120:121], v[34:35], v[8:9]
	v_cvt_pk_f32_fp8_sdwa v[120:121], v98 src0_sel:WORD_1
	v_pk_fma_f32 v[8:9], v[118:119], v[36:37], v[8:9]
	v_cvt_pk_f32_fp8_e32 v[118:119], v99
	v_pk_fma_f32 v[8:9], v[120:121], v[38:39], v[8:9]
	v_cvt_pk_f32_fp8_sdwa v[120:121], v99 src0_sel:WORD_1
	v_pk_fma_f32 v[8:9], v[118:119], v[40:41], v[8:9]
	s_nop 0
	v_pk_fma_f32 v[8:9], v[120:121], v[42:43], v[8:9]
	v_add_f32_e32 v129, v8, v9
	v_cvt_pk_f32_fp8_e32 v[118:119], v100
	v_cvt_pk_f32_fp8_sdwa v[120:121], v100 src0_sel:WORD_1
	s_nop 0
	v_pk_mul_f32 v[8:9], v[118:119], v[28:29]
	v_cvt_pk_f32_fp8_e32 v[118:119], v101
	v_pk_fma_f32 v[8:9], v[120:121], v[30:31], v[8:9]
	v_cvt_pk_f32_fp8_sdwa v[120:121], v101 src0_sel:WORD_1
	v_pk_fma_f32 v[8:9], v[118:119], v[32:33], v[8:9]
	v_cvt_pk_f32_fp8_e32 v[118:119], v102
	v_pk_fma_f32 v[8:9], v[120:121], v[34:35], v[8:9]
	v_cvt_pk_f32_fp8_sdwa v[120:121], v102 src0_sel:WORD_1
	v_pk_fma_f32 v[8:9], v[118:119], v[36:37], v[8:9]
	v_cvt_pk_f32_fp8_e32 v[118:119], v103
	v_pk_fma_f32 v[8:9], v[120:121], v[38:39], v[8:9]
	v_cvt_pk_f32_fp8_sdwa v[120:121], v103 src0_sel:WORD_1
	v_pk_fma_f32 v[8:9], v[118:119], v[40:41], v[8:9]
	s_nop 0
	v_pk_fma_f32 v[8:9], v[120:121], v[42:43], v[8:9]
	v_add_f32_e32 v130, v8, v9
	v_cvt_pk_f32_fp8_e32 v[118:119], v104
	v_cvt_pk_f32_fp8_sdwa v[120:121], v104 src0_sel:WORD_1
	s_nop 0
	v_pk_mul_f32 v[8:9], v[118:119], v[28:29]
	v_cvt_pk_f32_fp8_e32 v[118:119], v105
	v_pk_fma_f32 v[8:9], v[120:121], v[30:31], v[8:9]
	v_cvt_pk_f32_fp8_sdwa v[120:121], v105 src0_sel:WORD_1
	v_pk_fma_f32 v[8:9], v[118:119], v[32:33], v[8:9]
	v_cvt_pk_f32_fp8_e32 v[118:119], v106
	v_pk_fma_f32 v[8:9], v[120:121], v[34:35], v[8:9]
	v_cvt_pk_f32_fp8_sdwa v[120:121], v106 src0_sel:WORD_1
	v_pk_fma_f32 v[8:9], v[118:119], v[36:37], v[8:9]
	v_cvt_pk_f32_fp8_e32 v[118:119], v107
	v_pk_fma_f32 v[8:9], v[120:121], v[38:39], v[8:9]
	v_cvt_pk_f32_fp8_sdwa v[120:121], v107 src0_sel:WORD_1
	v_pk_fma_f32 v[8:9], v[118:119], v[40:41], v[8:9]
	s_nop 0
	v_pk_fma_f32 v[8:9], v[120:121], v[42:43], v[8:9]
	v_add_f32_e32 v131, v8, v9
	v_cndmask_b32_e32 v116, v124, v128, vcc
	v_cndmask_b32_e32 v117, v128, v124, vcc
	v_cndmask_b32_e32 v118, v125, v129, vcc
	v_cndmask_b32_e32 v119, v129, v125, vcc
	v_cndmask_b32_e32 v120, v126, v130, vcc
	v_cndmask_b32_e32 v121, v130, v126, vcc
	v_cndmask_b32_e32 v122, v127, v131, vcc
	v_cndmask_b32_e32 v123, v131, v127, vcc
	v_add_f32_dpp v124, v117, v116 row_half_mirror row_mask:0xf bank_mask:0xf
	v_add_f32_dpp v125, v119, v118 row_half_mirror row_mask:0xf bank_mask:0xf
	v_add_f32_dpp v126, v121, v120 row_half_mirror row_mask:0xf bank_mask:0xf
	v_add_f32_dpp v127, v123, v122 row_half_mirror row_mask:0xf bank_mask:0xf
	v_cndmask_b32_e64 v116, v124, v126, s[34:35]
	v_cndmask_b32_e64 v117, v126, v124, s[34:35]
	v_cndmask_b32_e64 v118, v125, v127, s[34:35]
	v_cndmask_b32_e64 v119, v127, v125, s[34:35]
	s_nop 0
	v_add_f32_dpp v124, v117, v116 quad_perm:[2,3,0,1] row_mask:0xf bank_mask:0xf
	v_add_f32_dpp v125, v119, v118 quad_perm:[2,3,0,1] row_mask:0xf bank_mask:0xf
	v_cndmask_b32_e64 v116, v124, v125, s[30:31]
	v_cndmask_b32_e64 v117, v125, v124, s[30:31]
	s_nop 1
	v_add_f32_dpp v7, v117, v116 quad_perm:[1,0,3,2] row_mask:0xf bank_mask:0xf
	s_lshl_b32 s0, s38, 9
	v_add_u32_e32 v19, s0, v3
	global_store_dword v19, v5, s[46:47]
	global_store_dword v19, v7, s[46:47] offset:256
	s_add_i32 s38, s38, s39
	s_cmp_gt_u32 s38, 0xffff
	s_cbranch_scc1 .Lpu_part_next

.Lpu_tokB_in:
	v_lshlrev_b32_e32 v28, 16, v20
	v_and_b32_e32 v29, 0xffff0000, v20
	v_lshlrev_b32_e32 v30, 16, v21
	v_and_b32_e32 v31, 0xffff0000, v21
	v_lshlrev_b32_e32 v32, 16, v22
	v_and_b32_e32 v33, 0xffff0000, v22
	v_lshlrev_b32_e32 v34, 16, v23
	v_and_b32_e32 v35, 0xffff0000, v23
	v_lshlrev_b32_e32 v36, 16, v24
	v_and_b32_e32 v37, 0xffff0000, v24
	v_lshlrev_b32_e32 v38, 16, v25
	v_and_b32_e32 v39, 0xffff0000, v25
	v_lshlrev_b32_e32 v40, 16, v26
	v_and_b32_e32 v41, 0xffff0000, v26
	v_lshlrev_b32_e32 v42, 16, v27
	v_and_b32_e32 v43, 0xffff0000, v27
	ds_bpermute_b32 v124, v4, v10
	ds_bpermute_b32 v125, v12, v10
	ds_bpermute_b32 v126, v13, v10
	ds_bpermute_b32 v127, v14, v10
	ds_bpermute_b32 v128, v15, v10
	ds_bpermute_b32 v129, v16, v10
	ds_bpermute_b32 v130, v17, v10
	ds_bpermute_b32 v131, v18, v10
	s_waitcnt lgkmcnt(0)
	v_lshl_add_u32 v124, v124, 7, v1
	v_lshl_add_u32 v125, v125, 7, v1
	v_lshl_add_u32 v126, v126, 7, v1
	v_lshl_add_u32 v127, v127, 7, v1
	v_lshl_add_u32 v128, v128, 7, v1
	v_lshl_add_u32 v129, v129, 7, v1
	v_lshl_add_u32 v130, v130, 7, v1
	v_lshl_add_u32 v131, v131, 7, v1
	global_load_dwordx4 v[44:47], v124, s[44:45]
	global_load_dwordx4 v[48:51], v125, s[44:45]
	global_load_dwordx4 v[52:55], v126, s[44:45]
	global_load_dwordx4 v[56:59], v127, s[44:45]
	global_load_dwordx4 v[60:63], v128, s[44:45]
	global_load_dwordx4 v[64:67], v129, s[44:45]
	global_load_dwordx4 v[68:71], v130, s[44:45]
	global_load_dwordx4 v[72:75], v131, s[44:45]
	ds_bpermute_b32 v124, v4, v11
	ds_bpermute_b32 v125, v12, v11
	ds_bpermute_b32 v126, v13, v11
	ds_bpermute_b32 v127, v14, v11
	ds_bpermute_b32 v128, v15, v11
	ds_bpermute_b32 v129, v16, v11
	ds_bpermute_b32 v130, v17, v11
	ds_bpermute_b32 v131, v18, v11
	s_waitcnt lgkmcnt(0)
	v_lshl_add_u32 v124, v124, 7, v1
	v_lshl_add_u32 v125, v125, 7, v1
	v_lshl_add_u32 v126, v126, 7, v1
	v_lshl_add_u32 v127, v127, 7, v1
	v_lshl_add_u32 v128, v128, 7, v1
	v_lshl_add_u32 v129, v129, 7, v1
	v_lshl_add_u32 v130, v130, 7, v1
	v_lshl_add_u32 v131, v131, 7, v1
	global_load_dwordx4 v[76:79], v124, s[44:45]
	global_load_dwordx4 v[80:83], v125, s[44:45]
	global_load_dwordx4 v[84:87], v126, s[44:45]
	global_load_dwordx4 v[88:91], v127, s[44:45]
	global_load_dwordx4 v[92:95], v128, s[44:45]
	global_load_dwordx4 v[96:99], v129, s[44:45]
	global_load_dwordx4 v[100:103], v130, s[44:45]
	global_load_dwordx4 v[104:107], v131, s[44:45]
	s_lshl_b32 s1, s39, 1
	s_add_i32 s1, s1, s38
	s_min_u32 s1, s1, 0xffff
	s_lshl_b32 s0, s1, 9
	v_add_u32_e32 v0, s0, v6
	global_load_dword v10, v0, s[42:43]
	global_load_dword v11, v0, s[42:43] offset:256
	s_lshl_b32 s0, s1, 11
	v_add_u32_e32 v0, s0, v2
	global_load_dwordx4 v[20:23], v0, s[48:49]
	global_load_dwordx4 v[24:27], v0, s[48:49] offset:16
	v_cvt_pk_f32_fp8_e32 v[118:119], v198
	v_cvt_pk_f32_fp8_sdwa v[120:121], v198 src0_sel:WORD_1
	s_nop 0
	v_pk_mul_f32 v[8:9], v[118:119], v[108:109]
	v_cvt_pk_f32_fp8_e32 v[118:119], v199
	v_pk_fma_f32 v[8:9], v[120:121], v[110:111], v[8:9]
	v_cvt_pk_f32_fp8_sdwa v[120:121], v199 src0_sel:WORD_1
	v_pk_fma_f32 v[8:9], v[118:119], v[112:113], v[8:9]
	v_cvt_pk_f32_fp8_e32 v[118:119], v200
	v_pk_fma_f32 v[8:9], v[120:121], v[114:115], v[8:9]
	v_cvt_pk_f32_fp8_sdwa v[120:121], v200 src0_sel:WORD_1
	v_pk_fma_f32 v[8:9], v[118:119], v[238:239], v[8:9]
	v_cvt_pk_f32_fp8_e32 v[118:119], v201
	v_pk_fma_f32 v[8:9], v[120:121], v[240:241], v[8:9]
	v_cvt_pk_f32_fp8_sdwa v[120:121], v201 src0_sel:WORD_1
	v_pk_fma_f32 v[8:9], v[118:119], v[242:243], v[8:9]
	s_nop 0
	v_pk_fma_f32 v[8:9], v[120:121], v[244:245], v[8:9]
	v_add_f32_e32 v124, v8, v9
	v_cvt_pk_f32_fp8_e32 v[118:119], v202
	v_cvt_pk_f32_fp8_sdwa v[120:121], v202 src0_sel:WORD_1
	s_nop 0
	v_pk_mul_f32 v[8:9], v[118:119], v[108:109]
	v_cvt_pk_f32_fp8_e32 v[118:119], v203
	v_pk_fma_f32 v[8:9], v[120:121], v[110:111], v[8:9]
	v_cvt_pk_f32_fp8_sdwa v[120:121], v203 src0_sel:WORD_1
	v_pk_fma_f32 v[8:9], v[118:119], v[112:113], v[8:9]
	v_cvt_pk_f32_fp8_e32 v[118:119], v204
	v_pk_fma_f32 v[8:9], v[120:121], v[114:115], v[8:9]
	v_cvt_pk_f32_fp8_sdwa v[120:121], v204 src0_sel:WORD_1
	v_pk_fma_f32 v[8:9], v[118:119], v[238:239], v[8:9]
	v_cvt_pk_f32_fp8_e32 v[118:119], v205
	v_pk_fma_f32 v[8:9], v[120:121], v[240:241], v[8:9]
	v_cvt_pk_f32_fp8_sdwa v[120:121], v205 src0_sel:WORD_1
	v_pk_fma_f32 v[8:9], v[118:119], v[242:243], v[8:9]
	s_nop 0
	v_pk_fma_f32 v[8:9], v[120:121], v[244:245], v[8:9]
	v_add_f32_e32 v125, v8, v9
	v_cvt_pk_f32_fp8_e32 v[118:119], v206
	v_cvt_pk_f32_fp8_sdwa v[120:121], v206 src0_sel:WORD_1
	s_nop 0
	v_pk_mul_f32 v[8:9], v[118:119], v[108:109]
	v_cvt_pk_f32_fp8_e32 v[118:119], v207
	v_pk_fma_f32 v[8:9], v[120:121], v[110:111], v[8:9]
	v_cvt_pk_f32_fp8_sdwa v[120:121], v207 src0_sel:WORD_1
	v_pk_fma_f32 v[8:9], v[118:119], v[112:113], v[8:9]
	v_cvt_pk_f32_fp8_e32 v[118:119], v208
	v_pk_fma_f32 v[8:9], v[120:121], v[114:115], v[8:9]
	v_cvt_pk_f32_fp8_sdwa v[120:121], v208 src0_sel:WORD_1
	v_pk_fma_f32 v[8:9], v[118:119], v[238:239], v[8:9]
	v_cvt_pk_f32_fp8_e32 v[118:119], v209
	v_pk_fma_f32 v[8:9], v[120:121], v[240:241], v[8:9]
	v_cvt_pk_f32_fp8_sdwa v[120:121], v209 src0_sel:WORD_1
	v_pk_fma_f32 v[8:9], v[118:119], v[242:243], v[8:9]
	s_nop 0
	v_pk_fma_f32 v[8:9], v[120:121], v[244:245], v[8:9]
	v_add_f32_e32 v126, v8, v9
	v_cvt_pk_f32_fp8_e32 v[118:119], v210
	v_cvt_pk_f32_fp8_sdwa v[120:121], v210 src0_sel:WORD_1
	s_nop 0
	v_pk_mul_f32 v[8:9], v[118:119], v[108:109]
	v_cvt_pk_f32_fp8_e32 v[118:119], v211
	v_pk_fma_f32 v[8:9], v[120:121], v[110:111], v[8:9]
	v_cvt_pk_f32_fp8_sdwa v[120:121], v211 src0_sel:WORD_1
	v_pk_fma_f32 v[8:9], v[118:119], v[112:113], v[8:9]
	v_cvt_pk_f32_fp8_e32 v[118:119], v212
	v_pk_fma_f32 v[8:9], v[120:121], v[114:115], v[8:9]
	v_cvt_pk_f32_fp8_sdwa v[120:121], v212 src0_sel:WORD_1
	v_pk_fma_f32 v[8:9], v[118:119], v[238:239], v[8:9]
	v_cvt_pk_f32_fp8_e32 v[118:119], v213
	v_pk_fma_f32 v[8:9], v[120:121], v[240:241], v[8:9]
	v_cvt_pk_f32_fp8_sdwa v[120:121], v213 src0_sel:WORD_1
	v_pk_fma_f32 v[8:9], v[118:119], v[242:243], v[8:9]
	s_nop 0
	v_pk_fma_f32 v[8:9], v[120:121], v[244:245], v[8:9]
	v_add_f32_e32 v127, v8, v9
	v_cvt_pk_f32_fp8_e32 v[118:119], v214
	v_cvt_pk_f32_fp8_sdwa v[120:121], v214 src0_sel:WORD_1
	s_nop 0
	v_pk_mul_f32 v[8:9], v[118:119], v[108:109]
	v_cvt_pk_f32_fp8_e32 v[118:119], v215
	v_pk_fma_f32 v[8:9], v[120:121], v[110:111], v[8:9]
	v_cvt_pk_f32_fp8_sdwa v[120:121], v215 src0_sel:WORD_1
	v_pk_fma_f32 v[8:9], v[118:119], v[112:113], v[8:9]
	v_cvt_pk_f32_fp8_e32 v[118:119], v216
	v_pk_fma_f32 v[8:9], v[120:121], v[114:115], v[8:9]
	v_cvt_pk_f32_fp8_sdwa v[120:121], v216 src0_sel:WORD_1
	v_pk_fma_f32 v[8:9], v[118:119], v[238:239], v[8:9]
	v_cvt_pk_f32_fp8_e32 v[118:119], v217
	v_pk_fma_f32 v[8:9], v[120:121], v[240:241], v[8:9]
	v_cvt_pk_f32_fp8_sdwa v[120:121], v217 src0_sel:WORD_1
	v_pk_fma_f32 v[8:9], v[118:119], v[242:243], v[8:9]
	s_nop 0
	v_pk_fma_f32 v[8:9], v[120:121], v[244:245], v[8:9]
	v_add_f32_e32 v128, v8, v9
	v_cvt_pk_f32_fp8_e32 v[118:119], v218
	v_cvt_pk_f32_fp8_sdwa v[120:121], v218 src0_sel:WORD_1
	s_nop 0
	v_pk_mul_f32 v[8:9], v[118:119], v[108:109]
	v_cvt_pk_f32_fp8_e32 v[118:119], v219
	v_pk_fma_f32 v[8:9], v[120:121], v[110:111], v[8:9]
	v_cvt_pk_f32_fp8_sdwa v[120:121], v219 src0_sel:WORD_1
	v_pk_fma_f32 v[8:9], v[118:119], v[112:113], v[8:9]
	v_cvt_pk_f32_fp8_e32 v[118:119], v220
	v_pk_fma_f32 v[8:9], v[120:121], v[114:115], v[8:9]
	v_cvt_pk_f32_fp8_sdwa v[120:121], v220 src0_sel:WORD_1
	v_pk_fma_f32 v[8:9], v[118:119], v[238:239], v[8:9]
	v_cvt_pk_f32_fp8_e32 v[118:119], v221
	v_pk_fma_f32 v[8:9], v[120:121], v[240:241], v[8:9]
	v_cvt_pk_f32_fp8_sdwa v[120:121], v221 src0_sel:WORD_1
	v_pk_fma_f32 v[8:9], v[118:119], v[242:243], v[8:9]
	s_nop 0
	v_pk_fma_f32 v[8:9], v[120:121], v[244:245], v[8:9]
	v_add_f32_e32 v129, v8, v9
	v_cvt_pk_f32_fp8_e32 v[118:119], v222
	v_cvt_pk_f32_fp8_sdwa v[120:121], v222 src0_sel:WORD_1
	s_nop 0
	v_pk_mul_f32 v[8:9], v[118:119], v[108:109]
	v_cvt_pk_f32_fp8_e32 v[118:119], v223
	v_pk_fma_f32 v[8:9], v[120:121], v[110:111], v[8:9]
	v_cvt_pk_f32_fp8_sdwa v[120:121], v223 src0_sel:WORD_1
	v_pk_fma_f32 v[8:9], v[118:119], v[112:113], v[8:9]
	v_cvt_pk_f32_fp8_e32 v[118:119], v224
	v_pk_fma_f32 v[8:9], v[120:121], v[114:115], v[8:9]
	v_cvt_pk_f32_fp8_sdwa v[120:121], v224 src0_sel:WORD_1
	v_pk_fma_f32 v[8:9], v[118:119], v[238:239], v[8:9]
	v_cvt_pk_f32_fp8_e32 v[118:119], v225
	v_pk_fma_f32 v[8:9], v[120:121], v[240:241], v[8:9]
	v_cvt_pk_f32_fp8_sdwa v[120:121], v225 src0_sel:WORD_1
	v_pk_fma_f32 v[8:9], v[118:119], v[242:243], v[8:9]
	s_nop 0
	v_pk_fma_f32 v[8:9], v[120:121], v[244:245], v[8:9]
	v_add_f32_e32 v130, v8, v9
	v_cvt_pk_f32_fp8_e32 v[118:119], v226
	v_cvt_pk_f32_fp8_sdwa v[120:121], v226 src0_sel:WORD_1
	s_nop 0
	v_pk_mul_f32 v[8:9], v[118:119], v[108:109]
	v_cvt_pk_f32_fp8_e32 v[118:119], v227
	v_pk_fma_f32 v[8:9], v[120:121], v[110:111], v[8:9]
	v_cvt_pk_f32_fp8_sdwa v[120:121], v227 src0_sel:WORD_1
	v_pk_fma_f32 v[8:9], v[118:119], v[112:113], v[8:9]
	v_cvt_pk_f32_fp8_e32 v[118:119], v228
	v_pk_fma_f32 v[8:9], v[120:121], v[114:115], v[8:9]
	v_cvt_pk_f32_fp8_sdwa v[120:121], v228 src0_sel:WORD_1
	v_pk_fma_f32 v[8:9], v[118:119], v[238:239], v[8:9]
	v_cvt_pk_f32_fp8_e32 v[118:119], v229
	v_pk_fma_f32 v[8:9], v[120:121], v[240:241], v[8:9]
	v_cvt_pk_f32_fp8_sdwa v[120:121], v229 src0_sel:WORD_1
	v_pk_fma_f32 v[8:9], v[118:119], v[242:243], v[8:9]
	s_nop 0
	v_pk_fma_f32 v[8:9], v[120:121], v[244:245], v[8:9]
	v_add_f32_e32 v131, v8, v9
	v_cndmask_b32_e32 v116, v124, v128, vcc
	v_cndmask_b32_e32 v117, v128, v124, vcc
	v_cndmask_b32_e32 v118, v125, v129, vcc
	v_cndmask_b32_e32 v119, v129, v125, vcc
	v_cndmask_b32_e32 v120, v126, v130, vcc
	v_cndmask_b32_e32 v121, v130, v126, vcc
	v_cndmask_b32_e32 v122, v127, v131, vcc
	v_cndmask_b32_e32 v123, v131, v127, vcc
	v_add_f32_dpp v124, v117, v116 row_half_mirror row_mask:0xf bank_mask:0xf
	v_add_f32_dpp v125, v119, v118 row_half_mirror row_mask:0xf bank_mask:0xf
	v_add_f32_dpp v126, v121, v120 row_half_mirror row_mask:0xf bank_mask:0xf
	v_add_f32_dpp v127, v123, v122 row_half_mirror row_mask:0xf bank_mask:0xf
	v_cndmask_b32_e64 v116, v124, v126, s[34:35]
	v_cndmask_b32_e64 v117, v126, v124, s[34:35]
	v_cndmask_b32_e64 v118, v125, v127, s[34:35]
	v_cndmask_b32_e64 v119, v127, v125, s[34:35]
	s_nop 0
	v_add_f32_dpp v124, v117, v116 quad_perm:[2,3,0,1] row_mask:0xf bank_mask:0xf
	v_add_f32_dpp v125, v119, v118 quad_perm:[2,3,0,1] row_mask:0xf bank_mask:0xf
	v_cndmask_b32_e64 v116, v124, v125, s[30:31]
	v_cndmask_b32_e64 v117, v125, v124, s[30:31]
	s_nop 1
	v_add_f32_dpp v5, v117, v116 quad_perm:[1,0,3,2] row_mask:0xf bank_mask:0xf
	v_cvt_pk_f32_fp8_e32 v[118:119], v230
	v_cvt_pk_f32_fp8_sdwa v[120:121], v230 src0_sel:WORD_1
	s_nop 0
	v_pk_mul_f32 v[8:9], v[118:119], v[108:109]
	v_cvt_pk_f32_fp8_e32 v[118:119], v231
	v_pk_fma_f32 v[8:9], v[120:121], v[110:111], v[8:9]
	v_cvt_pk_f32_fp8_sdwa v[120:121], v231 src0_sel:WORD_1
	v_pk_fma_f32 v[8:9], v[118:119], v[112:113], v[8:9]
	v_cvt_pk_f32_fp8_e32 v[118:119], v232
	v_pk_fma_f32 v[8:9], v[120:121], v[114:115], v[8:9]
	v_cvt_pk_f32_fp8_sdwa v[120:121], v232 src0_sel:WORD_1
	v_pk_fma_f32 v[8:9], v[118:119], v[238:239], v[8:9]
	v_cvt_pk_f32_fp8_e32 v[118:119], v233
	v_pk_fma_f32 v[8:9], v[120:121], v[240:241], v[8:9]
	v_cvt_pk_f32_fp8_sdwa v[120:121], v233 src0_sel:WORD_1
	v_pk_fma_f32 v[8:9], v[118:119], v[242:243], v[8:9]
	s_nop 0
	v_pk_fma_f32 v[8:9], v[120:121], v[244:245], v[8:9]
	v_add_f32_e32 v124, v8, v9
	v_cvt_pk_f32_fp8_e32 v[118:119], v234
	v_cvt_pk_f32_fp8_sdwa v[120:121], v234 src0_sel:WORD_1
	s_nop 0
	v_pk_mul_f32 v[8:9], v[118:119], v[108:109]
	v_cvt_pk_f32_fp8_e32 v[118:119], v235
	v_pk_fma_f32 v[8:9], v[120:121], v[110:111], v[8:9]
	v_cvt_pk_f32_fp8_sdwa v[120:121], v235 src0_sel:WORD_1
	v_pk_fma_f32 v[8:9], v[118:119], v[112:113], v[8:9]
	v_cvt_pk_f32_fp8_e32 v[118:119], v236
	v_pk_fma_f32 v[8:9], v[120:121], v[114:115], v[8:9]
	v_cvt_pk_f32_fp8_sdwa v[120:121], v236 src0_sel:WORD_1
	v_pk_fma_f32 v[8:9], v[118:119], v[238:239], v[8:9]
	v_cvt_pk_f32_fp8_e32 v[118:119], v237
	v_pk_fma_f32 v[8:9], v[120:121], v[240:241], v[8:9]
	v_cvt_pk_f32_fp8_sdwa v[120:121], v237 src0_sel:WORD_1
	v_pk_fma_f32 v[8:9], v[118:119], v[242:243], v[8:9]
	s_nop 0
	v_pk_fma_f32 v[8:9], v[120:121], v[244:245], v[8:9]
	v_add_f32_e32 v125, v8, v9
	v_cvt_pk_f32_fp8_e32 v[118:119], v138
	v_cvt_pk_f32_fp8_sdwa v[120:121], v138 src0_sel:WORD_1
	s_nop 0
	v_pk_mul_f32 v[8:9], v[118:119], v[108:109]
	v_cvt_pk_f32_fp8_e32 v[118:119], v139
	v_pk_fma_f32 v[8:9], v[120:121], v[110:111], v[8:9]
	v_cvt_pk_f32_fp8_sdwa v[120:121], v139 src0_sel:WORD_1
	v_pk_fma_f32 v[8:9], v[118:119], v[112:113], v[8:9]
	v_cvt_pk_f32_fp8_e32 v[118:119], v140
	v_pk_fma_f32 v[8:9], v[120:121], v[114:115], v[8:9]
	v_cvt_pk_f32_fp8_sdwa v[120:121], v140 src0_sel:WORD_1
	v_pk_fma_f32 v[8:9], v[118:119], v[238:239], v[8:9]
	v_cvt_pk_f32_fp8_e32 v[118:119], v141
	v_pk_fma_f32 v[8:9], v[120:121], v[240:241], v[8:9]
	v_cvt_pk_f32_fp8_sdwa v[120:121], v141 src0_sel:WORD_1
	v_pk_fma_f32 v[8:9], v[118:119], v[242:243], v[8:9]
	s_nop 0
	v_pk_fma_f32 v[8:9], v[120:121], v[244:245], v[8:9]
	v_add_f32_e32 v126, v8, v9
	v_cvt_pk_f32_fp8_e32 v[118:119], v142
	v_cvt_pk_f32_fp8_sdwa v[120:121], v142 src0_sel:WORD_1
	s_nop 0
	v_pk_mul_f32 v[8:9], v[118:119], v[108:109]
	v_cvt_pk_f32_fp8_e32 v[118:119], v143
	v_pk_fma_f32 v[8:9], v[120:121], v[110:111], v[8:9]
	v_cvt_pk_f32_fp8_sdwa v[120:121], v143 src0_sel:WORD_1
	v_pk_fma_f32 v[8:9], v[118:119], v[112:113], v[8:9]
	v_cvt_pk_f32_fp8_e32 v[118:119], v144
	v_pk_fma_f32 v[8:9], v[120:121], v[114:115], v[8:9]
	v_cvt_pk_f32_fp8_sdwa v[120:121], v144 src0_sel:WORD_1
	v_pk_fma_f32 v[8:9], v[118:119], v[238:239], v[8:9]
	v_cvt_pk_f32_fp8_e32 v[118:119], v145
	v_pk_fma_f32 v[8:9], v[120:121], v[240:241], v[8:9]
	v_cvt_pk_f32_fp8_sdwa v[120:121], v145 src0_sel:WORD_1
	v_pk_fma_f32 v[8:9], v[118:119], v[242:243], v[8:9]
	s_nop 0
	v_pk_fma_f32 v[8:9], v[120:121], v[244:245], v[8:9]
	v_add_f32_e32 v127, v8, v9
	v_cvt_pk_f32_fp8_e32 v[118:119], v146
	v_cvt_pk_f32_fp8_sdwa v[120:121], v146 src0_sel:WORD_1
	s_nop 0
	v_pk_mul_f32 v[8:9], v[118:119], v[108:109]
	v_cvt_pk_f32_fp8_e32 v[118:119], v147
	v_pk_fma_f32 v[8:9], v[120:121], v[110:111], v[8:9]
	v_cvt_pk_f32_fp8_sdwa v[120:121], v147 src0_sel:WORD_1
	v_pk_fma_f32 v[8:9], v[118:119], v[112:113], v[8:9]
	v_cvt_pk_f32_fp8_e32 v[118:119], v148
	v_pk_fma_f32 v[8:9], v[120:121], v[114:115], v[8:9]
	v_cvt_pk_f32_fp8_sdwa v[120:121], v148 src0_sel:WORD_1
	v_pk_fma_f32 v[8:9], v[118:119], v[238:239], v[8:9]
	v_cvt_pk_f32_fp8_e32 v[118:119], v149
	v_pk_fma_f32 v[8:9], v[120:121], v[240:241], v[8:9]
	v_cvt_pk_f32_fp8_sdwa v[120:121], v149 src0_sel:WORD_1
	v_pk_fma_f32 v[8:9], v[118:119], v[242:243], v[8:9]
	s_nop 0
	v_pk_fma_f32 v[8:9], v[120:121], v[244:245], v[8:9]
	v_add_f32_e32 v128, v8, v9
	v_cvt_pk_f32_fp8_e32 v[118:119], v150
	v_cvt_pk_f32_fp8_sdwa v[120:121], v150 src0_sel:WORD_1
	s_nop 0
	v_pk_mul_f32 v[8:9], v[118:119], v[108:109]
	v_cvt_pk_f32_fp8_e32 v[118:119], v151
	v_pk_fma_f32 v[8:9], v[120:121], v[110:111], v[8:9]
	v_cvt_pk_f32_fp8_sdwa v[120:121], v151 src0_sel:WORD_1
	v_pk_fma_f32 v[8:9], v[118:119], v[112:113], v[8:9]
	v_cvt_pk_f32_fp8_e32 v[118:119], v152
	v_pk_fma_f32 v[8:9], v[120:121], v[114:115], v[8:9]
	v_cvt_pk_f32_fp8_sdwa v[120:121], v152 src0_sel:WORD_1
	v_pk_fma_f32 v[8:9], v[118:119], v[238:239], v[8:9]
	v_cvt_pk_f32_fp8_e32 v[118:119], v153
	v_pk_fma_f32 v[8:9], v[120:121], v[240:241], v[8:9]
	v_cvt_pk_f32_fp8_sdwa v[120:121], v153 src0_sel:WORD_1
	v_pk_fma_f32 v[8:9], v[118:119], v[242:243], v[8:9]
	s_nop 0
	v_pk_fma_f32 v[8:9], v[120:121], v[244:245], v[8:9]
	v_add_f32_e32 v129, v8, v9
	v_cvt_pk_f32_fp8_e32 v[118:119], v154
	v_cvt_pk_f32_fp8_sdwa v[120:121], v154 src0_sel:WORD_1
	s_nop 0
	v_pk_mul_f32 v[8:9], v[118:119], v[108:109]
	v_cvt_pk_f32_fp8_e32 v[118:119], v155
	v_pk_fma_f32 v[8:9], v[120:121], v[110:111], v[8:9]
	v_cvt_pk_f32_fp8_sdwa v[120:121], v155 src0_sel:WORD_1
	v_pk_fma_f32 v[8:9], v[118:119], v[112:113], v[8:9]
	v_cvt_pk_f32_fp8_e32 v[118:119], v156
	v_pk_fma_f32 v[8:9], v[120:121], v[114:115], v[8:9]
	v_cvt_pk_f32_fp8_sdwa v[120:121], v156 src0_sel:WORD_1
	v_pk_fma_f32 v[8:9], v[118:119], v[238:239], v[8:9]
	v_cvt_pk_f32_fp8_e32 v[118:119], v157
	v_pk_fma_f32 v[8:9], v[120:121], v[240:241], v[8:9]
	v_cvt_pk_f32_fp8_sdwa v[120:121], v157 src0_sel:WORD_1
	v_pk_fma_f32 v[8:9], v[118:119], v[242:243], v[8:9]
	s_nop 0
	v_pk_fma_f32 v[8:9], v[120:121], v[244:245], v[8:9]
	v_add_f32_e32 v130, v8, v9
	v_cvt_pk_f32_fp8_e32 v[118:119], v158
	v_cvt_pk_f32_fp8_sdwa v[120:121], v158 src0_sel:WORD_1
	s_nop 0
	v_pk_mul_f32 v[8:9], v[118:119], v[108:109]
	v_cvt_pk_f32_fp8_e32 v[118:119], v159
	v_pk_fma_f32 v[8:9], v[120:121], v[110:111], v[8:9]
	v_cvt_pk_f32_fp8_sdwa v[120:121], v159 src0_sel:WORD_1
	v_pk_fma_f32 v[8:9], v[118:119], v[112:113], v[8:9]
	v_cvt_pk_f32_fp8_e32 v[118:119], v160
	v_pk_fma_f32 v[8:9], v[120:121], v[114:115], v[8:9]
	v_cvt_pk_f32_fp8_sdwa v[120:121], v160 src0_sel:WORD_1
	v_pk_fma_f32 v[8:9], v[118:119], v[238:239], v[8:9]
	v_cvt_pk_f32_fp8_e32 v[118:119], v161
	v_pk_fma_f32 v[8:9], v[120:121], v[240:241], v[8:9]
	v_cvt_pk_f32_fp8_sdwa v[120:121], v161 src0_sel:WORD_1
	v_pk_fma_f32 v[8:9], v[118:119], v[242:243], v[8:9]
	s_nop 0
	v_pk_fma_f32 v[8:9], v[120:121], v[244:245], v[8:9]
	v_add_f32_e32 v131, v8, v9
	v_cndmask_b32_e32 v116, v124, v128, vcc
	v_cndmask_b32_e32 v117, v128, v124, vcc
	v_cndmask_b32_e32 v118, v125, v129, vcc
	v_cndmask_b32_e32 v119, v129, v125, vcc
	v_cndmask_b32_e32 v120, v126, v130, vcc
	v_cndmask_b32_e32 v121, v130, v126, vcc
	v_cndmask_b32_e32 v122, v127, v131, vcc
	v_cndmask_b32_e32 v123, v131, v127, vcc
	v_add_f32_dpp v124, v117, v116 row_half_mirror row_mask:0xf bank_mask:0xf
	v_add_f32_dpp v125, v119, v118 row_half_mirror row_mask:0xf bank_mask:0xf
	v_add_f32_dpp v126, v121, v120 row_half_mirror row_mask:0xf bank_mask:0xf
	v_add_f32_dpp v127, v123, v122 row_half_mirror row_mask:0xf bank_mask:0xf
	v_cndmask_b32_e64 v116, v124, v126, s[34:35]
	v_cndmask_b32_e64 v117, v126, v124, s[34:35]
	v_cndmask_b32_e64 v118, v125, v127, s[34:35]
	v_cndmask_b32_e64 v119, v127, v125, s[34:35]
	s_nop 0
	v_add_f32_dpp v124, v117, v116 quad_perm:[2,3,0,1] row_mask:0xf bank_mask:0xf
	v_add_f32_dpp v125, v119, v118 quad_perm:[2,3,0,1] row_mask:0xf bank_mask:0xf
	v_cndmask_b32_e64 v116, v124, v125, s[30:31]
	v_cndmask_b32_e64 v117, v125, v124, s[30:31]
	s_nop 1
	v_add_f32_dpp v7, v117, v116 quad_perm:[1,0,3,2] row_mask:0xf bank_mask:0xf
	s_lshl_b32 s0, s38, 9
	v_add_u32_e32 v19, s0, v3
	global_store_dword v19, v5, s[46:47]
	global_store_dword v19, v7, s[46:47] offset:256
	s_add_i32 s38, s38, s39
	s_cmp_gt_u32 s38, 0xffff
	s_cbranch_scc1 .Lpu_part_next
	s_branch .Lpu_tokA
